# P3 load balance: batch-1 attention q-block pairs re-matched (126/134 key tiles) so workgroups that also run an SSM state item carry 254 tiles and the others 266
# baseline (speedup 1.0000x reference)
.LBB0_555:
	s_or_b64 exec, exec, s[4:5]
	v_ashrrev_i32_e32 v8, 8, v2
	s_waitcnt vmcnt(0)
	v_mul_f32_e32 v151, 0x3fb8aa3b, v4
	v_lshlrev_b32_e32 v3, 2, v2
	v_bfe_u32 v4, v2, 2, 2
	v_and_b32_e32 v6, 31, v2
	v_bfe_u32 v5, v2, 5, 1
	v_and_or_b32 v3, v3, 12, v4
	v_lshlrev_b32_e32 v9, 3, v8
	v_lshlrev_b32_e32 v4, 8, v6
	v_or_b32_e32 v10, v9, v5
	v_bitop3_b32 v9, v9, v3, v5 bitop3:0x36
	v_lshl_add_u32 v152, v9, 4, v4
	v_bitop3_b32 v9, v10, v3, 2 bitop3:0x36
	s_add_i32 s0, s57, 0xffffff80
	v_and_b32_e32 v150, 63, v2
	v_lshl_add_u32 v153, v9, 4, v4
	v_bitop3_b32 v9, v10, v3, 4 bitop3:0x36
	v_bitop3_b32 v3, v10, v3, 6 bitop3:0x36
	s_bfe_u32 s1, s0, 0x50003
	s_and_b32 s4, s56, 7
	s_lshl_b32 s0, s0, 5
	v_lshl_add_u32 v154, v9, 4, v4
	v_lshl_add_u32 v155, v3, 4, v4
	v_bfe_u32 v3, v150, 2, 2
	v_lshlrev_b32_e32 v9, 10, v5
	v_lshrrev_b32_e32 v11, 3, v2
	s_lshl_b32 s10, s4, 8
	s_and_b32 s60, s0, 0x2000
	v_lshl_or_b32 v9, v3, 8, v9
	v_and_b32_e32 v11, 2, v11
	v_bfe_u32 v12, v2, 1, 1
	v_lshlrev_b32_e32 v14, 6, v3
	v_or_b32_e32 v3, 2, v5
	v_lshlrev_b32_e32 v10, 3, v2
	v_bitop3_b32 v3, v11, v3, v12 bitop3:0x36
	s_cmp_gt_u32 s1, 15
	v_and_b32_e32 v10, 8, v10
	v_lshlrev_b32_e32 v3, 4, v3
	s_cselect_b64 s[90:91], -1, 0
	s_lshl_b32 s0, s1, 1
	v_bitop3_b32 v13, v11, v5, v12 bitop3:0x36
	v_or3_b32 v3, v14, v3, v10
	s_lshl_b32 s11, s8, 7
	s_or_b32 s28, s0, 1
	s_xor_b32 s29, s0, 63
	s_sub_i32 s30, s0, 32
	s_sub_i32 s31, 0x5e, s0
	s_cmp_eq_u32 s60, 0
	s_cbranch_scc1 .Lrebal_skip
	s_lshl_b32 s28, s1, 2
	s_sub_i32 s29, 63, s28
	s_sub_i32 s30, s28, 64
	s_sub_i32 s31, 0x7d, s28
	s_add_i32 s28, s28, 2
.Lrebal_skip:
	s_lshl_b32 s8, s8, 8
	v_readlane_b32 s48, v230, 34
	v_ashrrev_i32_e32 v1, 6, v2
	v_bfe_u32 v4, v2, 2, 4
	v_lshlrev_b32_e32 v13, 4, v13
	v_add_u32_e32 v157, v3, v9
	v_bfe_u32 v3, v2, 4, 2
	v_and_b32_e32 v11, 15, v2
	v_lshlrev_b32_e32 v2, 6, v8
	v_readlane_b32 s49, v230, 35
	s_add_u32 s6, s48, s8
	v_or3_b32 v13, v9, v13, v10
	v_lshl_or_b32 v10, v1, 3, v3
	v_ashrrev_i32_e32 v3, 31, v2
	s_mul_i32 s13, s60, 0x3000
	v_lshlrev_b32_e32 v12, 1, v1
	s_addc_u32 s7, s49, 0
	v_and_b32_e32 v4, 12, v4
	v_and_b32_e32 v12, 2, v12
	v_lshl_add_u64 v[2:3], v[2:3], 1, s[6:7]
	s_add_i32 s6, s48, s13
	v_or_b32_e32 v15, v4, v12
	v_bitop3_b32 v4, v4, v11, v12 bitop3:0x36
	v_mul_lo_u32 v10, v10, s33
	s_addk_i32 s6, 0x800
	v_readlane_b32 s64, v230, 18
	v_lshl_or_b32 v162, v4, 4, v10
	v_bitop3_b32 v4, v15, v11, 1 bitop3:0x36
	s_add_i32 s7, s6, s8
	v_readlane_b32 s74, v230, 28
	v_lshl_or_b32 v4, v4, 4, v10
	v_readlane_b32 s50, v230, 36
	s_sub_i32 s36, s7, s74
	v_and_b32_e32 v7, 3, v1
	v_lshlrev_b32_e32 v160, 11, v1
	v_add_u32_e32 v163, 0xc000, v4
	v_cmp_gt_u32_e64 s[4:5], 4, v1
	v_readlane_b32 s51, v230, 37
	v_lshlrev_b32_e32 v4, 4, v5
	v_mov_b32_e32 v5, v0
	s_add_u32 s94, s50, s8
	v_readlane_b32 s7, v229, 20
	v_lshlrev_b32_e32 v1, 2, v6
	s_movk_i32 s0, 0x80
	v_lshl_add_u64 v[144:145], v[2:3], 0, v[4:5]
	s_addc_u32 s95, s51, 0
	s_add_i32 s27, s7, s10
	v_sub_u32_e32 v1, v4, v1
	v_lshlrev_b32_e32 v2, 7, v7
	v_readlane_b32 s7, v229, 21
	v_add_u32_e32 v9, 0x800, v157
	v_lshlrev_b32_e32 v158, 5, v7
	v_bitop3_b32 v168, v13, s0, v14 bitop3:0x36
	s_movk_i32 s0, 0xc0
	v_sub_u32_e32 v1, v1, v2
	s_add_i32 s35, s7, s10
	v_or_b32_e32 v156, v13, v14
	v_or_b32_e32 v159, v158, v6
	v_add_u32_e32 v161, 0x4000, v160
	v_or_b32_e32 v164, 0x400, v160
	v_add_u32_e32 v165, 0x4400, v160
	v_bitop3_b32 v166, v13, 64, v14 bitop3:0x36
	v_xor_b32_e32 v167, 64, v9
	v_xor_b32_e32 v169, 0x80, v9
	v_bitop3_b32 v170, v13, s0, v14 bitop3:0x36
	v_xor_b32_e32 v171, 0xc0, v9
	v_cmp_lt_u32_e64 s[92:93], 1, v7
	v_lshlrev_b32_e32 v172, 14, v7
	v_cmp_eq_u32_e64 s[0:1], 1, v8
	s_add_i32 s37, s36, 0x800
	s_add_i32 s27, s27, s6
	v_add_u32_e32 v173, 0x243fc, v1
	s_add_i32 s35, s35, s6
	s_mov_b64 s[50:51], -1
	s_lshl_b32 s22, s11, 1
	v_readlane_b32 s52, v230, 38
	v_readlane_b32 s53, v230, 39
	v_readlane_b32 s54, v230, 40
	v_readlane_b32 s55, v230, 41
	v_readlane_b32 s65, v230, 19
	v_readlane_b32 s66, v230, 20
	v_readlane_b32 s67, v230, 21
	v_readlane_b32 s68, v230, 22
	v_readlane_b32 s69, v230, 23
	v_readlane_b32 s70, v230, 24
	v_readlane_b32 s71, v230, 25
	v_readlane_b32 s72, v230, 26
	v_readlane_b32 s73, v230, 27
	v_readlane_b32 s75, v230, 29
	v_readlane_b32 s76, v230, 30
	v_readlane_b32 s77, v230, 31
	v_readlane_b32 s78, v230, 32
	v_readlane_b32 s79, v230, 33
	s_branch .LBB0_557
